# o30 + nt (streaming) stores for the bf16 weights written by the GU1/GU2 idle-tail converters (less pollution of the XCD L2 shared with the running GEMM tiles)
# baseline (speedup 1.0000x reference)
.Lw1d_loop:
	v_readfirstlane_b32 s98, v18
	s_nop 3
	s_cmpk_ge_u32 s98, 0x780
	s_cbranch_scc1 .Lw1d_done
	s_cmpk_ge_u32 s98, 0x580
	s_cbranch_scc1 .Lwo_item
	s_lshr_b32 s99, s98, 4
	s_and_b32 s100, s98, 15
	s_lshl_b32 s101, s99, 19
	s_lshl_b32 s0, s100, 9
	s_add_u32 s0, s0, s101
	s_add_u32 s0, s8, s0
	s_addc_u32 s1, s9, 0
	s_mul_i32 s2, s100, 0x160000
	s_lshl_b32 s3, s99, 7
	s_add_u32 s2, s2, s3
	s_add_u32 s2, s2, 0x2d60200
	s_add_u32 s2, s86, s2
	s_addc_u32 s3, s87, 0
	s_add_u32 s4, s2, 0xb0000
	s_addc_u32 s5, s3, 0
	global_load_dwordx4 v[154:157], v8, s[0:1] nt
	global_load_dwordx4 v[204:207], v8, s[0:1] offset:256 nt
	s_add_u32 s0, s0, 0x2000
	s_addc_u32 s1, s1, 0
	global_load_dwordx4 v[158:161], v8, s[0:1] nt
	global_load_dwordx4 v[208:211], v8, s[0:1] offset:256 nt
	s_add_u32 s0, s0, 0x2000
	s_addc_u32 s1, s1, 0
	global_load_dwordx4 v[162:165], v8, s[0:1] nt
	global_load_dwordx4 v[212:215], v8, s[0:1] offset:256 nt
	s_add_u32 s0, s0, 0x2000
	s_addc_u32 s1, s1, 0
	global_load_dwordx4 v[166:169], v8, s[0:1] nt
	global_load_dwordx4 v[216:219], v8, s[0:1] offset:256 nt
	s_add_u32 s0, s0, 0x2000
	s_addc_u32 s1, s1, 0
	global_load_dwordx4 v[170:173], v8, s[0:1] nt
	global_load_dwordx4 v[220:223], v8, s[0:1] offset:256 nt
	s_add_u32 s0, s0, 0x2000
	s_addc_u32 s1, s1, 0
	global_load_dwordx4 v[174:177], v8, s[0:1] nt
	global_load_dwordx4 v[224:227], v8, s[0:1] offset:256 nt
	s_add_u32 s0, s0, 0x2000
	s_addc_u32 s1, s1, 0
	global_load_dwordx4 v[178:181], v8, s[0:1] nt
	global_load_dwordx4 v[228:231], v8, s[0:1] offset:256 nt
	s_add_u32 s0, s0, 0x2000
	s_addc_u32 s1, s1, 0
	global_load_dwordx4 v[182:185], v8, s[0:1] nt
	global_load_dwordx4 v[232:235], v8, s[0:1] offset:256 nt
	s_add_u32 s0, s0, 0x2000
	s_addc_u32 s1, s1, 0
	global_load_dwordx4 v[186:189], v8, s[0:1] nt
	global_load_dwordx4 v[236:239], v8, s[0:1] offset:256 nt
	s_add_u32 s0, s0, 0x2000
	s_addc_u32 s1, s1, 0
	global_load_dwordx4 v[190:193], v8, s[0:1] nt
	global_load_dwordx4 v[240:243], v8, s[0:1] offset:256 nt
	s_add_u32 s0, s0, 0x2000
	s_addc_u32 s1, s1, 0
	global_load_dwordx4 v[194:197], v8, s[0:1] nt
	global_load_dwordx4 v[244:247], v8, s[0:1] offset:256 nt
	s_add_u32 s0, s0, 0x2000
	s_addc_u32 s1, s1, 0
	global_load_dwordx4 v[198:201], v8, s[0:1] nt
	global_load_dwordx4 v[248:251], v8, s[0:1] offset:256 nt
	s_add_u32 s0, s0, 0x2000
	s_addc_u32 s1, s1, 0
	global_load_dwordx4 v[130:133], v8, s[0:1] nt
	global_load_dwordx4 v[50:53], v8, s[0:1] offset:256 nt
	s_add_u32 s0, s0, 0x2000
	s_addc_u32 s1, s1, 0
	global_load_dwordx4 v[134:137], v8, s[0:1] nt
	global_load_dwordx4 v[54:57], v8, s[0:1] offset:256 nt
	s_add_u32 s0, s0, 0x2000
	s_addc_u32 s1, s1, 0
	global_load_dwordx4 v[138:141], v8, s[0:1] nt
	global_load_dwordx4 v[58:61], v8, s[0:1] offset:256 nt
	s_add_u32 s0, s0, 0x2000
	s_addc_u32 s1, s1, 0
	global_load_dwordx4 v[142:145], v8, s[0:1] nt
	global_load_dwordx4 v[62:65], v8, s[0:1] offset:256 nt
	s_mov_b64 exec, 1
	global_atomic_add v18, v16, v17, s[6:7] sc0
	s_mov_b64 exec, -1
	s_waitcnt vmcnt(1)
	v_cvt_pk_bf16_f32 v20, v154, v158
	v_cvt_pk_bf16_f32 v21, v162, v166
	v_cvt_pk_bf16_f32 v22, v170, v174
	v_cvt_pk_bf16_f32 v23, v178, v182
	global_store_dwordx4 v12, v[20:23], s[2:3] nt
	v_cvt_pk_bf16_f32 v24, v186, v190
	v_cvt_pk_bf16_f32 v25, v194, v198
	v_cvt_pk_bf16_f32 v26, v130, v134
	v_cvt_pk_bf16_f32 v27, v138, v142
	global_store_dwordx4 v12, v[24:27], s[2:3] offset:16 nt
	v_cvt_pk_bf16_f32 v28, v155, v159
	v_cvt_pk_bf16_f32 v29, v163, v167
	v_cvt_pk_bf16_f32 v30, v171, v175
	v_cvt_pk_bf16_f32 v31, v179, v183
	global_store_dwordx4 v13, v[28:31], s[2:3] nt
	v_cvt_pk_bf16_f32 v32, v187, v191
	v_cvt_pk_bf16_f32 v33, v195, v199
	v_cvt_pk_bf16_f32 v34, v131, v135
	v_cvt_pk_bf16_f32 v35, v139, v143
	global_store_dwordx4 v13, v[32:35], s[2:3] offset:16 nt
	v_cvt_pk_bf16_f32 v36, v156, v160
	v_cvt_pk_bf16_f32 v37, v164, v168
	v_cvt_pk_bf16_f32 v38, v172, v176
	v_cvt_pk_bf16_f32 v39, v180, v184
	global_store_dwordx4 v14, v[36:39], s[2:3] nt
	v_cvt_pk_bf16_f32 v40, v188, v192
	v_cvt_pk_bf16_f32 v41, v196, v200
	v_cvt_pk_bf16_f32 v42, v132, v136
	v_cvt_pk_bf16_f32 v43, v140, v144
	global_store_dwordx4 v14, v[40:43], s[2:3] offset:16 nt
	v_cvt_pk_bf16_f32 v20, v157, v161
	v_cvt_pk_bf16_f32 v21, v165, v169
	v_cvt_pk_bf16_f32 v22, v173, v177
	v_cvt_pk_bf16_f32 v23, v181, v185
	global_store_dwordx4 v15, v[20:23], s[2:3] nt
	v_cvt_pk_bf16_f32 v24, v189, v193
	v_cvt_pk_bf16_f32 v25, v197, v201
	v_cvt_pk_bf16_f32 v26, v133, v137
	v_cvt_pk_bf16_f32 v27, v141, v145
	global_store_dwordx4 v15, v[24:27], s[2:3] offset:16 nt
	v_cvt_pk_bf16_f32 v28, v204, v208
	v_cvt_pk_bf16_f32 v29, v212, v216
	v_cvt_pk_bf16_f32 v30, v220, v224
	v_cvt_pk_bf16_f32 v31, v228, v232
	global_store_dwordx4 v12, v[28:31], s[4:5] nt
	v_cvt_pk_bf16_f32 v32, v236, v240
	v_cvt_pk_bf16_f32 v33, v244, v248
	v_cvt_pk_bf16_f32 v34, v50, v54
	v_cvt_pk_bf16_f32 v35, v58, v62
	global_store_dwordx4 v12, v[32:35], s[4:5] offset:16 nt
	v_cvt_pk_bf16_f32 v36, v205, v209
	v_cvt_pk_bf16_f32 v37, v213, v217
	v_cvt_pk_bf16_f32 v38, v221, v225
	v_cvt_pk_bf16_f32 v39, v229, v233
	global_store_dwordx4 v13, v[36:39], s[4:5] nt
	v_cvt_pk_bf16_f32 v40, v237, v241
	v_cvt_pk_bf16_f32 v41, v245, v249
	v_cvt_pk_bf16_f32 v42, v51, v55
	v_cvt_pk_bf16_f32 v43, v59, v63
	global_store_dwordx4 v13, v[40:43], s[4:5] offset:16 nt
	v_cvt_pk_bf16_f32 v20, v206, v210
	v_cvt_pk_bf16_f32 v21, v214, v218
	v_cvt_pk_bf16_f32 v22, v222, v226
	v_cvt_pk_bf16_f32 v23, v230, v234
	global_store_dwordx4 v14, v[20:23], s[4:5] nt
	v_cvt_pk_bf16_f32 v24, v238, v242
	v_cvt_pk_bf16_f32 v25, v246, v250
	v_cvt_pk_bf16_f32 v26, v52, v56
	v_cvt_pk_bf16_f32 v27, v60, v64
	global_store_dwordx4 v14, v[24:27], s[4:5] offset:16 nt
	v_cvt_pk_bf16_f32 v28, v207, v211
	v_cvt_pk_bf16_f32 v29, v215, v219
	v_cvt_pk_bf16_f32 v30, v223, v227
	v_cvt_pk_bf16_f32 v31, v231, v235
	global_store_dwordx4 v15, v[28:31], s[4:5] nt
	v_cvt_pk_bf16_f32 v32, v239, v243
	v_cvt_pk_bf16_f32 v33, v247, v251
	v_cvt_pk_bf16_f32 v34, v53, v57
	v_cvt_pk_bf16_f32 v35, v61, v65
	global_store_dwordx4 v15, v[32:35], s[4:5] offset:16 nt
	s_waitcnt vmcnt(16)
	s_branch .Lw1d_loop
.Lwo_item:
	s_sub_u32 s98, s98, 0x580
	s_lshr_b32 s99, s98, 4
	s_and_b32 s100, s98, 15
	s_lshl_b32 s101, s99, 19
	s_lshl_b32 s0, s100, 9
	s_add_u32 s0, s0, s101
	s_add_u32 s0, s10, s0
	s_addc_u32 s1, s11, 0
	s_lshl_b32 s2, s100, 19
	s_lshl_b32 s3, s99, 7
	s_add_u32 s2, s2, s3
	s_add_u32 s2, s2, 0x8460200
	s_add_u32 s2, s86, s2
	s_addc_u32 s3, s87, 0
	s_add_u32 s4, s2, 0x40000
	s_addc_u32 s5, s3, 0
	global_load_dwordx4 v[154:157], v8, s[0:1] nt
	global_load_dwordx4 v[204:207], v8, s[0:1] offset:256 nt
	s_add_u32 s0, s0, 0x2000
	s_addc_u32 s1, s1, 0
	global_load_dwordx4 v[158:161], v8, s[0:1] nt
	global_load_dwordx4 v[208:211], v8, s[0:1] offset:256 nt
	s_add_u32 s0, s0, 0x2000
	s_addc_u32 s1, s1, 0
	global_load_dwordx4 v[162:165], v8, s[0:1] nt
	global_load_dwordx4 v[212:215], v8, s[0:1] offset:256 nt
	s_add_u32 s0, s0, 0x2000
	s_addc_u32 s1, s1, 0
	global_load_dwordx4 v[166:169], v8, s[0:1] nt
	global_load_dwordx4 v[216:219], v8, s[0:1] offset:256 nt
	s_add_u32 s0, s0, 0x2000
	s_addc_u32 s1, s1, 0
	global_load_dwordx4 v[170:173], v8, s[0:1] nt
	global_load_dwordx4 v[220:223], v8, s[0:1] offset:256 nt
	s_add_u32 s0, s0, 0x2000
	s_addc_u32 s1, s1, 0
	global_load_dwordx4 v[174:177], v8, s[0:1] nt
	global_load_dwordx4 v[224:227], v8, s[0:1] offset:256 nt
	s_add_u32 s0, s0, 0x2000
	s_addc_u32 s1, s1, 0
	global_load_dwordx4 v[178:181], v8, s[0:1] nt
	global_load_dwordx4 v[228:231], v8, s[0:1] offset:256 nt
	s_add_u32 s0, s0, 0x2000
	s_addc_u32 s1, s1, 0
	global_load_dwordx4 v[182:185], v8, s[0:1] nt
	global_load_dwordx4 v[232:235], v8, s[0:1] offset:256 nt
	s_add_u32 s0, s0, 0x2000
	s_addc_u32 s1, s1, 0
	global_load_dwordx4 v[186:189], v8, s[0:1] nt
	global_load_dwordx4 v[236:239], v8, s[0:1] offset:256 nt
	s_add_u32 s0, s0, 0x2000
	s_addc_u32 s1, s1, 0
	global_load_dwordx4 v[190:193], v8, s[0:1] nt
	global_load_dwordx4 v[240:243], v8, s[0:1] offset:256 nt
	s_add_u32 s0, s0, 0x2000
	s_addc_u32 s1, s1, 0
	global_load_dwordx4 v[194:197], v8, s[0:1] nt
	global_load_dwordx4 v[244:247], v8, s[0:1] offset:256 nt
	s_add_u32 s0, s0, 0x2000
	s_addc_u32 s1, s1, 0
	global_load_dwordx4 v[198:201], v8, s[0:1] nt
	global_load_dwordx4 v[248:251], v8, s[0:1] offset:256 nt
	s_add_u32 s0, s0, 0x2000
	s_addc_u32 s1, s1, 0
	global_load_dwordx4 v[130:133], v8, s[0:1] nt
	global_load_dwordx4 v[50:53], v8, s[0:1] offset:256 nt
	s_add_u32 s0, s0, 0x2000
	s_addc_u32 s1, s1, 0
	global_load_dwordx4 v[134:137], v8, s[0:1] nt
	global_load_dwordx4 v[54:57], v8, s[0:1] offset:256 nt
	s_add_u32 s0, s0, 0x2000
	s_addc_u32 s1, s1, 0
	global_load_dwordx4 v[138:141], v8, s[0:1] nt
	global_load_dwordx4 v[58:61], v8, s[0:1] offset:256 nt
	s_add_u32 s0, s0, 0x2000
	s_addc_u32 s1, s1, 0
	global_load_dwordx4 v[142:145], v8, s[0:1] nt
	global_load_dwordx4 v[62:65], v8, s[0:1] offset:256 nt
	s_mov_b64 exec, 1
	global_atomic_add v18, v16, v17, s[6:7] sc0
	s_mov_b64 exec, -1
	s_waitcnt vmcnt(1)
	v_cvt_pk_bf16_f32 v20, v154, v158
	v_cvt_pk_bf16_f32 v21, v162, v166
	v_cvt_pk_bf16_f32 v22, v170, v174
	v_cvt_pk_bf16_f32 v23, v178, v182
	global_store_dwordx4 v44, v[20:23], s[2:3] nt
	v_cvt_pk_bf16_f32 v24, v186, v190
	v_cvt_pk_bf16_f32 v25, v194, v198
	v_cvt_pk_bf16_f32 v26, v130, v134
	v_cvt_pk_bf16_f32 v27, v138, v142
	global_store_dwordx4 v44, v[24:27], s[2:3] offset:16 nt
	v_cvt_pk_bf16_f32 v28, v155, v159
	v_cvt_pk_bf16_f32 v29, v163, v167
	v_cvt_pk_bf16_f32 v30, v171, v175
	v_cvt_pk_bf16_f32 v31, v179, v183
	global_store_dwordx4 v45, v[28:31], s[2:3] nt
	v_cvt_pk_bf16_f32 v32, v187, v191
	v_cvt_pk_bf16_f32 v33, v195, v199
	v_cvt_pk_bf16_f32 v34, v131, v135
	v_cvt_pk_bf16_f32 v35, v139, v143
	global_store_dwordx4 v45, v[32:35], s[2:3] offset:16 nt
	v_cvt_pk_bf16_f32 v36, v156, v160
	v_cvt_pk_bf16_f32 v37, v164, v168
	v_cvt_pk_bf16_f32 v38, v172, v176
	v_cvt_pk_bf16_f32 v39, v180, v184
	global_store_dwordx4 v46, v[36:39], s[2:3] nt
	v_cvt_pk_bf16_f32 v40, v188, v192
	v_cvt_pk_bf16_f32 v41, v196, v200
	v_cvt_pk_bf16_f32 v42, v132, v136
	v_cvt_pk_bf16_f32 v43, v140, v144
	global_store_dwordx4 v46, v[40:43], s[2:3] offset:16 nt
	v_cvt_pk_bf16_f32 v20, v157, v161
	v_cvt_pk_bf16_f32 v21, v165, v169
	v_cvt_pk_bf16_f32 v22, v173, v177
	v_cvt_pk_bf16_f32 v23, v181, v185
	global_store_dwordx4 v47, v[20:23], s[2:3] nt
	v_cvt_pk_bf16_f32 v24, v189, v193
	v_cvt_pk_bf16_f32 v25, v197, v201
	v_cvt_pk_bf16_f32 v26, v133, v137
	v_cvt_pk_bf16_f32 v27, v141, v145
	global_store_dwordx4 v47, v[24:27], s[2:3] offset:16 nt
	v_cvt_pk_bf16_f32 v28, v204, v208
	v_cvt_pk_bf16_f32 v29, v212, v216
	v_cvt_pk_bf16_f32 v30, v220, v224
	v_cvt_pk_bf16_f32 v31, v228, v232
	global_store_dwordx4 v44, v[28:31], s[4:5] nt
	v_cvt_pk_bf16_f32 v32, v236, v240
	v_cvt_pk_bf16_f32 v33, v244, v248
	v_cvt_pk_bf16_f32 v34, v50, v54
	v_cvt_pk_bf16_f32 v35, v58, v62
	global_store_dwordx4 v44, v[32:35], s[4:5] offset:16 nt
	v_cvt_pk_bf16_f32 v36, v205, v209
	v_cvt_pk_bf16_f32 v37, v213, v217
	v_cvt_pk_bf16_f32 v38, v221, v225
	v_cvt_pk_bf16_f32 v39, v229, v233
	global_store_dwordx4 v45, v[36:39], s[4:5] nt
	v_cvt_pk_bf16_f32 v40, v237, v241
	v_cvt_pk_bf16_f32 v41, v245, v249
	v_cvt_pk_bf16_f32 v42, v51, v55
	v_cvt_pk_bf16_f32 v43, v59, v63
	global_store_dwordx4 v45, v[40:43], s[4:5] offset:16 nt
	v_cvt_pk_bf16_f32 v20, v206, v210
	v_cvt_pk_bf16_f32 v21, v214, v218
	v_cvt_pk_bf16_f32 v22, v222, v226
	v_cvt_pk_bf16_f32 v23, v230, v234
	global_store_dwordx4 v46, v[20:23], s[4:5] nt
	v_cvt_pk_bf16_f32 v24, v238, v242
	v_cvt_pk_bf16_f32 v25, v246, v250
	v_cvt_pk_bf16_f32 v26, v52, v56
	v_cvt_pk_bf16_f32 v27, v60, v64
	global_store_dwordx4 v46, v[24:27], s[4:5] offset:16 nt
	v_cvt_pk_bf16_f32 v28, v207, v211
	v_cvt_pk_bf16_f32 v29, v215, v219
	v_cvt_pk_bf16_f32 v30, v223, v227
	v_cvt_pk_bf16_f32 v31, v231, v235
	global_store_dwordx4 v47, v[28:31], s[4:5] nt
	v_cvt_pk_bf16_f32 v32, v239, v243
	v_cvt_pk_bf16_f32 v33, v247, v251
	v_cvt_pk_bf16_f32 v34, v53, v57
	v_cvt_pk_bf16_f32 v35, v61, v65
	global_store_dwordx4 v47, v[32:35], s[4:5] offset:16 nt
	s_waitcnt vmcnt(16)
	s_branch .Lw1d_loop

.Lw2d_loop:
	v_readfirstlane_b32 s98, v18
	s_nop 3
	s_cmpk_ge_u32 s98, 0x580
	s_cbranch_scc1 .Lw2d_done
	s_lshr_b32 s99, s98, 4
	s_and_b32 s100, s98, 15
	s_lshl_b32 s101, s99, 19
	s_lshl_b32 s0, s100, 9
	s_add_u32 s0, s0, s101
	s_add_u32 s0, s10, s0
	s_addc_u32 s1, s11, 0
	s_mul_i32 s2, s100, 0x160000
	s_lshl_b32 s3, s99, 7
	s_add_u32 s2, s2, s3
	s_add_u32 s2, s2, 0xb860200
	s_add_u32 s2, s86, s2
	s_addc_u32 s3, s87, 0
	s_add_u32 s6, s2, 0xb0000
	s_addc_u32 s7, s3, 0
	global_load_dwordx4 v[154:157], v8, s[0:1] nt
	global_load_dwordx4 v[204:207], v8, s[0:1] offset:256 nt
	s_add_u32 s0, s0, 0x2000
	s_addc_u32 s1, s1, 0
	global_load_dwordx4 v[158:161], v8, s[0:1] nt
	global_load_dwordx4 v[208:211], v8, s[0:1] offset:256 nt
	s_add_u32 s0, s0, 0x2000
	s_addc_u32 s1, s1, 0
	global_load_dwordx4 v[162:165], v8, s[0:1] nt
	global_load_dwordx4 v[212:215], v8, s[0:1] offset:256 nt
	s_add_u32 s0, s0, 0x2000
	s_addc_u32 s1, s1, 0
	global_load_dwordx4 v[166:169], v8, s[0:1] nt
	global_load_dwordx4 v[216:219], v8, s[0:1] offset:256 nt
	s_add_u32 s0, s0, 0x2000
	s_addc_u32 s1, s1, 0
	global_load_dwordx4 v[170:173], v8, s[0:1] nt
	global_load_dwordx4 v[220:223], v8, s[0:1] offset:256 nt
	s_add_u32 s0, s0, 0x2000
	s_addc_u32 s1, s1, 0
	global_load_dwordx4 v[174:177], v8, s[0:1] nt
	global_load_dwordx4 v[224:227], v8, s[0:1] offset:256 nt
	s_add_u32 s0, s0, 0x2000
	s_addc_u32 s1, s1, 0
	global_load_dwordx4 v[178:181], v8, s[0:1] nt
	global_load_dwordx4 v[228:231], v8, s[0:1] offset:256 nt
	s_add_u32 s0, s0, 0x2000
	s_addc_u32 s1, s1, 0
	global_load_dwordx4 v[182:185], v8, s[0:1] nt
	global_load_dwordx4 v[232:235], v8, s[0:1] offset:256 nt
	s_add_u32 s0, s0, 0x2000
	s_addc_u32 s1, s1, 0
	global_load_dwordx4 v[186:189], v8, s[0:1] nt
	global_load_dwordx4 v[236:239], v8, s[0:1] offset:256 nt
	s_add_u32 s0, s0, 0x2000
	s_addc_u32 s1, s1, 0
	global_load_dwordx4 v[190:193], v8, s[0:1] nt
	global_load_dwordx4 v[240:243], v8, s[0:1] offset:256 nt
	s_add_u32 s0, s0, 0x2000
	s_addc_u32 s1, s1, 0
	global_load_dwordx4 v[194:197], v8, s[0:1] nt
	global_load_dwordx4 v[244:247], v8, s[0:1] offset:256 nt
	s_add_u32 s0, s0, 0x2000
	s_addc_u32 s1, s1, 0
	global_load_dwordx4 v[198:201], v8, s[0:1] nt
	global_load_dwordx4 v[248:251], v8, s[0:1] offset:256 nt
	s_add_u32 s0, s0, 0x2000
	s_addc_u32 s1, s1, 0
	global_load_dwordx4 v[130:133], v8, s[0:1] nt
	global_load_dwordx4 v[50:53], v8, s[0:1] offset:256 nt
	s_add_u32 s0, s0, 0x2000
	s_addc_u32 s1, s1, 0
	global_load_dwordx4 v[134:137], v8, s[0:1] nt
	global_load_dwordx4 v[54:57], v8, s[0:1] offset:256 nt
	s_add_u32 s0, s0, 0x2000
	s_addc_u32 s1, s1, 0
	global_load_dwordx4 v[138:141], v8, s[0:1] nt
	global_load_dwordx4 v[58:61], v8, s[0:1] offset:256 nt
	s_add_u32 s0, s0, 0x2000
	s_addc_u32 s1, s1, 0
	global_load_dwordx4 v[142:145], v8, s[0:1] nt
	global_load_dwordx4 v[62:65], v8, s[0:1] offset:256 nt
	s_mov_b64 exec, 1
	global_atomic_add v18, v16, v17, s[8:9] sc0
	s_mov_b64 exec, -1
	s_waitcnt vmcnt(1)
	v_cvt_pk_bf16_f32 v20, v154, v158
	v_cvt_pk_bf16_f32 v21, v162, v166
	v_cvt_pk_bf16_f32 v22, v170, v174
	v_cvt_pk_bf16_f32 v23, v178, v182
	global_store_dwordx4 v12, v[20:23], s[2:3] nt
	v_cvt_pk_bf16_f32 v24, v186, v190
	v_cvt_pk_bf16_f32 v25, v194, v198
	v_cvt_pk_bf16_f32 v26, v130, v134
	v_cvt_pk_bf16_f32 v27, v138, v142
	global_store_dwordx4 v12, v[24:27], s[2:3] offset:16 nt
	v_cvt_pk_bf16_f32 v28, v155, v159
	v_cvt_pk_bf16_f32 v29, v163, v167
	v_cvt_pk_bf16_f32 v30, v171, v175
	v_cvt_pk_bf16_f32 v31, v179, v183
	global_store_dwordx4 v13, v[28:31], s[2:3] nt
	v_cvt_pk_bf16_f32 v32, v187, v191
	v_cvt_pk_bf16_f32 v33, v195, v199
	v_cvt_pk_bf16_f32 v34, v131, v135
	v_cvt_pk_bf16_f32 v35, v139, v143
	global_store_dwordx4 v13, v[32:35], s[2:3] offset:16 nt
	v_cvt_pk_bf16_f32 v36, v156, v160
	v_cvt_pk_bf16_f32 v37, v164, v168
	v_cvt_pk_bf16_f32 v38, v172, v176
	v_cvt_pk_bf16_f32 v39, v180, v184
	global_store_dwordx4 v14, v[36:39], s[2:3] nt
	v_cvt_pk_bf16_f32 v40, v188, v192
	v_cvt_pk_bf16_f32 v41, v196, v200
	v_cvt_pk_bf16_f32 v42, v132, v136
	v_cvt_pk_bf16_f32 v43, v140, v144
	global_store_dwordx4 v14, v[40:43], s[2:3] offset:16 nt
	v_cvt_pk_bf16_f32 v20, v157, v161
	v_cvt_pk_bf16_f32 v21, v165, v169
	v_cvt_pk_bf16_f32 v22, v173, v177
	v_cvt_pk_bf16_f32 v23, v181, v185
	global_store_dwordx4 v15, v[20:23], s[2:3] nt
	v_cvt_pk_bf16_f32 v24, v189, v193
	v_cvt_pk_bf16_f32 v25, v197, v201
	v_cvt_pk_bf16_f32 v26, v133, v137
	v_cvt_pk_bf16_f32 v27, v141, v145
	global_store_dwordx4 v15, v[24:27], s[2:3] offset:16 nt
	v_cvt_pk_bf16_f32 v28, v204, v208
	v_cvt_pk_bf16_f32 v29, v212, v216
	v_cvt_pk_bf16_f32 v30, v220, v224
	v_cvt_pk_bf16_f32 v31, v228, v232
	global_store_dwordx4 v12, v[28:31], s[6:7] nt
	v_cvt_pk_bf16_f32 v32, v236, v240
	v_cvt_pk_bf16_f32 v33, v244, v248
	v_cvt_pk_bf16_f32 v34, v50, v54
	v_cvt_pk_bf16_f32 v35, v58, v62
	global_store_dwordx4 v12, v[32:35], s[6:7] offset:16 nt
	v_cvt_pk_bf16_f32 v36, v205, v209
	v_cvt_pk_bf16_f32 v37, v213, v217
	v_cvt_pk_bf16_f32 v38, v221, v225
	v_cvt_pk_bf16_f32 v39, v229, v233
	global_store_dwordx4 v13, v[36:39], s[6:7] nt
	v_cvt_pk_bf16_f32 v40, v237, v241
	v_cvt_pk_bf16_f32 v41, v245, v249
	v_cvt_pk_bf16_f32 v42, v51, v55
	v_cvt_pk_bf16_f32 v43, v59, v63
	global_store_dwordx4 v13, v[40:43], s[6:7] offset:16 nt
	v_cvt_pk_bf16_f32 v20, v206, v210
	v_cvt_pk_bf16_f32 v21, v214, v218
	v_cvt_pk_bf16_f32 v22, v222, v226
	v_cvt_pk_bf16_f32 v23, v230, v234
	global_store_dwordx4 v14, v[20:23], s[6:7] nt
	v_cvt_pk_bf16_f32 v24, v238, v242
	v_cvt_pk_bf16_f32 v25, v246, v250
	v_cvt_pk_bf16_f32 v26, v52, v56
	v_cvt_pk_bf16_f32 v27, v60, v64
	global_store_dwordx4 v14, v[24:27], s[6:7] offset:16 nt
	v_cvt_pk_bf16_f32 v28, v207, v211
	v_cvt_pk_bf16_f32 v29, v215, v219
	v_cvt_pk_bf16_f32 v30, v223, v227
	v_cvt_pk_bf16_f32 v31, v231, v235
	global_store_dwordx4 v15, v[28:31], s[6:7] nt
	v_cvt_pk_bf16_f32 v32, v239, v243
	v_cvt_pk_bf16_f32 v33, v247, v251
	v_cvt_pk_bf16_f32 v34, v53, v57
	v_cvt_pk_bf16_f32 v35, v61, v65
	global_store_dwordx4 v15, v[32:35], s[6:7] offset:16 nt
	s_waitcnt vmcnt(16)
	s_branch .Lw2d_loop
